# attention: 384-row K/V ring over 4 consecutive query blocks per workgroup, pipelined LDS fragment reads, MFMAs spread through the softmax VALU
# speedup vs baseline: 1.0278x; 1.0038x over previous
.LBB0_327:
	s_andn2_b64 vcc, exec, s[4:5]
	s_cbranch_vccnz .LBB0_800
	s_cmp_lt_i32 s96, 1
	s_mov_b64 s[4:5], -1
	s_cbranch_scc1 .LBB0_384
	s_cmp_eq_u32 s96, 1
	s_cbranch_scc0 .LBB0_383
	v_readlane_b32 s4, v253, 18
	v_mov_b32_e32 v1, v175
	v_readlane_b32 s5, v253, 19
	s_andn2_b64 vcc, exec, s[4:5]
	v_readfirstlane_b32 s3, v1
	s_cbranch_vccnz .LBB0_383
	v_writelane_b32 v255, s96, 7
	v_writelane_b32 v255, s97, 8
	v_writelane_b32 v255, s98, 9
	v_writelane_b32 v255, s99, 10
	v_writelane_b32 v255, s86, 0
	v_writelane_b32 v255, s87, 1
	v_writelane_b32 v255, s42, 11
	s_mov_b32 s5, 0
	v_lshrrev_b32_e32 v212, 6, v175
	s_lshl_b32 s4, s42, 8
	v_writelane_b32 v255, s5, 12
	v_readfirstlane_b32 s3, v212
	v_readlane_b32 s48, v254, 20
	v_readlane_b32 s49, v254, 21
	v_readlane_b32 s46, v254, 22
	v_readlane_b32 s47, v254, 23
	v_readlane_b32 s50, v254, 12
	v_readlane_b32 s51, v254, 13
	v_readlane_b32 s59, v253, 3
	s_mov_b32 s52, s31
	s_nop 3
	s_add_u32 s48, s48, s4
	s_addc_u32 s49, s49, 0
	s_add_u32 s46, s46, s4
	s_addc_u32 s47, s47, 0
	s_lshr_b32 s4, s4, 2
	s_add_u32 s50, s50, s4
	s_addc_u32 s51, s51, 0
	s_add_u32 s42, s36, 0x180000
	s_addc_u32 s43, s37, 0
	s_lshr_b32 s71, s3, 1
	s_and_b32 s70, s3, 1
	s_lshl_b32 s70, s70, 6
	s_movk_i32 s60, 0xc00
	v_and_b32_e32 v1, 31, v175
	v_bfe_u32 v2, v175, 5, 1
	v_lshlrev_b32_e32 v3, 2, v2
	v_sub_u32_e32 v15, v1, v3
	v_cmp_eq_u32_e64 s[66:67], 1, v2
	v_and_b32_e32 v212, 7, v175
	v_cmp_gt_u32_e64 s[62:63], 2, v212
	v_cmp_eq_u32_e64 s[64:65], 0, v212
	v_lshlrev_b32_e32 v4, 4, v212
	v_lshrrev_b32_e32 v172, 3, v175
	v_mov_b32_e32 v216, 0x90
	v_mad_u32_u24 v5, v172, v216, v4
	v_add_u32_e32 v7, 0xffffff80, v172
	v_lshlrev_b32_e32 v172, 4, v2
	v_mad_u32_u24 v8, v1, v216, v172
	v_bfe_u32 v172, v175, 2, 2
	v_add_u32_e32 v172, v172, v3
	v_bfe_u32 v217, v175, 4, 1
	v_lshlrev_b32_e32 v217, 5, v217
	v_and_b32_e32 v250, 3, v175
	v_lshl_add_u32 v217, v250, 3, v217
	v_mad_u32_u24 v9, v172, v216, v217
	v_add_u32_e32 v9, 0xd800, v9
	v_add_u32_e32 v212, s70, v1
	s_lshl_b32 s4, s71, 7
	v_lshlrev_b32_e32 v172, 4, v2
	v_add_u32_e32 v172, s4, v172
	v_mul_u32_u24_e32 v216, 0xc00, v212
	v_add_u32_e32 v10, v216, v172
	v_add_u32_e32 v11, 0x18000, v10
	v_lshlrev_b32_e32 v12, 6, v212
	v_lshl_add_u32 v13, v212, 11, v172
	v_add_u32_e32 v14, 0x10000, v13
	s_cmpk_lt_i32 s52, 0x100
	s_cbranch_scc0 .Lat_exit
.Lat_chunk:
	s_and_b32 s54, s52, 3
	s_bfe_u32 s85, s52, 0x40002
	s_lshr_b32 s55, s52, 6
	s_lshl_b32 s53, s85, 2
	s_mov_b32 s58, 0
	s_mul_i32 s4, s85, 11
	s_lshr_b32 s4, s4, 5
	s_mul_i32 s4, s4, 3
	s_sub_u32 s82, s85, s4
	s_lshl_b32 s4, s54, 2
	s_add_u32 s56, s4, s71
	s_lshl_b32 s6, s55, 13
	v_readlane_b32 s8, v254, 33
	v_readlane_b32 s9, v254, 34
	s_mul_i32 s10, s6, 0xc00
	s_lshl_b32 s13, s54, 7
	s_add_u32 s10, s10, s13
	s_nop 0
	s_add_u32 s38, s8, s10
	s_addc_u32 s39, s9, 0
.Lat_unit:
	s_lshl_b32 s5, s56, 2
	s_load_dword s11, s[50:51], s5
	s_lshl_b32 s6, s55, 13
	s_lshl_b32 s7, s53, 7
	s_mul_i32 s10, s7, 0xc00
	s_lshl_b32 s13, s54, 9
	s_add_u32 s10, s10, s13
	s_lshl_b32 s13, s54, 7
	s_sub_u32 s10, s10, s13
	s_add_u32 s40, s38, s10
	s_addc_u32 s41, s39, 0
	s_lshl_b32 s10, s53, 13
	s_add_u32 s72, s42, s10
	s_addc_u32 s73, s43, 0
	v_readlane_b32 s8, v253, 20
	v_readlane_b32 s9, v253, 21
	s_add_u32 s10, s6, s7
	s_lshl_b32 s10, s10, 11
	s_lshl_b32 s13, s54, 9
	s_add_u32 s10, s10, s13
	s_add_u32 s44, s8, s10
	s_addc_u32 s45, s9, 0
	s_add_u32 s4, s82, 2
	s_cmp_ge_u32 s4, 3
	s_cselect_b32 s5, 3, 0
	s_sub_u32 s4, s4, s5
	s_lshl_b32 s83, s4, 7
	s_cmp_eq_u32 s53, 0
	s_cselect_b32 s4, 128, 0
	s_sub_i32 s4, s4, s70
	s_max_i32 s4, s4, 0
	s_lshr_b32 s57, s4, 5
	s_movk_i32 s4, 0x100
	s_cmp_eq_u32 s53, 63
	s_cselect_b32 s4, s4, 0x180
	s_sub_u32 s4, s4, s70
	s_lshr_b32 s4, s4, 5
	s_min_u32 s68, s4, 10
	s_barrier
	v_add_u32_e32 v217, s7, v7
	s_cmp_lg_u32 s58, 0
	s_cbranch_scc1 .Lat_incr_1
	global_load_dwordx4 v[96:99], v10, s[40:41] offset:0
	global_load_dwordx4 v[100:103], v10, s[40:41] offset:32
	global_load_dwordx4 v[104:107], v10, s[40:41] offset:64
	global_load_dwordx4 v[108:111], v10, s[40:41] offset:96
	global_load_dwordx4 v[238:241], v11, s[40:41] offset:0
	global_load_dwordx4 v[242:245], v11, s[40:41] offset:32
	global_load_dwordx4 v[246:249], v11, s[40:41] offset:64
	global_load_dwordx4 v[222:225], v11, s[40:41] offset:96
	v_lshlrev_b32_e32 v212, 1, v4
	global_load_dwordx4 v[64:67], v212, s[46:47]
	global_load_dwordx4 v[68:71], v212, s[46:47] offset:16
	v_add_u32_e32 v212, 0, v217
	v_max_i32_e32 v212, 0, v212
	v_min_u32_e32 v212, 0x1fff, v212
	v_mul_lo_u32 v172, v212, s60
	v_add_u32_e32 v172, v172, v4
	v_lshlrev_b32_e32 v216, 6, v212
	global_load_dwordx4 v[16:19], v172, s[38:39] offset:2048
	global_load_dwordx4 v[20:23], v172, s[38:39] offset:2560
	s_mov_b64 exec, s[62:63]
	global_load_dwordx4 v[116:119], v216, s[42:43] offset:0
	global_load_dwordx4 v[120:123], v216, s[42:43] offset:16
	global_load_dwordx4 v[124:127], v216, s[42:43] offset:32
	global_load_dwordx4 v[128:131], v216, s[42:43] offset:48
	s_mov_b64 exec, -1
	v_add_u32_e32 v212, 64, v217
	v_max_i32_e32 v212, 0, v212
	v_min_u32_e32 v212, 0x1fff, v212
	v_mul_lo_u32 v172, v212, s60
	v_add_u32_e32 v172, v172, v4
	v_lshlrev_b32_e32 v216, 6, v212
	global_load_dwordx4 v[24:27], v172, s[38:39] offset:2048
	global_load_dwordx4 v[28:31], v172, s[38:39] offset:2560
	s_mov_b64 exec, s[62:63]
	global_load_dwordx4 v[132:135], v216, s[42:43] offset:0
	global_load_dwordx4 v[136:139], v216, s[42:43] offset:16
	global_load_dwordx4 v[140:143], v216, s[42:43] offset:32
	global_load_dwordx4 v[144:147], v216, s[42:43] offset:48
	s_mov_b64 exec, -1
	v_add_u32_e32 v212, 128, v217
	v_max_i32_e32 v212, 0, v212
	v_min_u32_e32 v212, 0x1fff, v212
	v_mul_lo_u32 v172, v212, s60
	v_add_u32_e32 v172, v172, v4
	v_lshlrev_b32_e32 v216, 6, v212
	global_load_dwordx4 v[32:35], v172, s[38:39] offset:2048
	global_load_dwordx4 v[36:39], v172, s[38:39] offset:2560
	s_mov_b64 exec, s[62:63]
	global_load_dwordx4 v[148:151], v216, s[42:43] offset:0
	global_load_dwordx4 v[152:155], v216, s[42:43] offset:16
	global_load_dwordx4 v[156:159], v216, s[42:43] offset:32
	global_load_dwordx4 v[160:163], v216, s[42:43] offset:48
	s_mov_b64 exec, -1
	v_add_u32_e32 v212, 192, v217
	v_max_i32_e32 v212, 0, v212
	v_min_u32_e32 v212, 0x1fff, v212
	v_mul_lo_u32 v172, v212, s60
	v_add_u32_e32 v172, v172, v4
	v_lshlrev_b32_e32 v216, 6, v212
	global_load_dwordx4 v[40:43], v172, s[38:39] offset:2048
	global_load_dwordx4 v[44:47], v172, s[38:39] offset:2560
	s_mov_b64 exec, s[62:63]
	global_load_dwordx4 v[164:167], v216, s[42:43] offset:0
	global_load_dwordx4 v[168:171], v216, s[42:43] offset:16
	global_load_dwordx4 v[176:179], v216, s[42:43] offset:32
	global_load_dwordx4 v[180:183], v216, s[42:43] offset:48
	s_mov_b64 exec, -1
	v_add_u32_e32 v212, 256, v217
	v_max_i32_e32 v212, 0, v212
	v_min_u32_e32 v212, 0x1fff, v212
	v_mul_lo_u32 v172, v212, s60
	v_add_u32_e32 v172, v172, v4
	v_lshlrev_b32_e32 v216, 6, v212
	global_load_dwordx4 v[48:51], v172, s[38:39] offset:2048
	global_load_dwordx4 v[52:55], v172, s[38:39] offset:2560
	s_mov_b64 exec, s[62:63]
	global_load_dwordx4 v[184:187], v216, s[42:43] offset:0
	global_load_dwordx4 v[188:191], v216, s[42:43] offset:16
	global_load_dwordx4 v[192:195], v216, s[42:43] offset:32
	global_load_dwordx4 v[196:199], v216, s[42:43] offset:48
	s_mov_b64 exec, -1
	v_add_u32_e32 v212, 320, v217
	v_max_i32_e32 v212, 0, v212
	v_min_u32_e32 v212, 0x1fff, v212
	v_mul_lo_u32 v172, v212, s60
	v_add_u32_e32 v172, v172, v4
	v_lshlrev_b32_e32 v216, 6, v212
	global_load_dwordx4 v[56:59], v172, s[38:39] offset:2048
	global_load_dwordx4 v[60:63], v172, s[38:39] offset:2560
	s_mov_b64 exec, s[62:63]
	global_load_dwordx4 v[200:203], v216, s[42:43] offset:0
	global_load_dwordx4 v[204:207], v216, s[42:43] offset:16
	global_load_dwordx4 v[208:211], v216, s[42:43] offset:32
	global_load_dwordx4 v[234:237], v216, s[42:43] offset:48
	s_mov_b64 exec, -1
	s_cmp_eq_u32 s53, 0
	s_cbranch_scc1 .Lat_skip0_2
	s_waitcnt vmcnt(30)
	v_lshlrev_b32_e32 v72, 16, v16
	v_and_b32_e32 v73, 0xffff0000, v16
	v_lshlrev_b32_e32 v74, 16, v17
	v_and_b32_e32 v75, 0xffff0000, v17
	v_lshlrev_b32_e32 v76, 16, v18
	v_and_b32_e32 v77, 0xffff0000, v18
	v_lshlrev_b32_e32 v78, 16, v19
	v_and_b32_e32 v79, 0xffff0000, v19
	v_mul_f32_e32 v88, v72, v72
	v_fmac_f32_e32 v88, v73, v73
	v_fmac_f32_e32 v88, v74, v74
	v_fmac_f32_e32 v88, v75, v75
	v_fmac_f32_e32 v88, v76, v76
	v_fmac_f32_e32 v88, v77, v77
	v_fmac_f32_e32 v88, v78, v78
	v_fmac_f32_e32 v88, v79, v79
	s_add_u32 s4, s83, 0
	s_cmpk_ge_u32 s4, 0x180
	s_cselect_b32 s5, 0x180, 0
	s_sub_u32 s4, s4, s5
	s_mul_i32 s4, s4, 0x90
	v_add_f32_dpp v88, v88, v88 quad_perm:[1,0,3,2] row_mask:0xf bank_mask:0xf
	s_nop 1
	v_add_f32_dpp v88, v88, v88 quad_perm:[2,3,0,1] row_mask:0xf bank_mask:0xf
	s_nop 1
	v_add_f32_dpp v88, v88, v88 row_half_mirror row_mask:0xf bank_mask:0xf
	s_nop 1
	v_fmamk_f32 v88, v88, 0x3c800000, v174
	v_rsq_f32_e32 v89, v88
	v_add_u32_e32 v212, s4, v5
	v_mul_f32_e32 v72, v72, v89
	v_mul_f32_e32 v73, v73, v89
	v_mul_f32_e32 v74, v74, v89
	v_mul_f32_e32 v75, v75, v89
	v_mul_f32_e32 v76, v76, v89
	v_mul_f32_e32 v77, v77, v89
	v_mul_f32_e32 v78, v78, v89
	v_mul_f32_e32 v79, v79, v89
	v_mul_f32_e32 v72, v72, v64
	v_mul_f32_e32 v73, v73, v65
	v_mul_f32_e32 v74, v74, v66
	v_mul_f32_e32 v75, v75, v67
	v_mul_f32_e32 v76, v76, v68
	v_mul_f32_e32 v77, v77, v69
	v_mul_f32_e32 v78, v78, v70
	v_mul_f32_e32 v79, v79, v71
	s_mov_b64 exec, s[62:63]
	s_nop 4
	v_mov_b32_dpp v80, v72 quad_perm:[1,0,3,2] row_mask:0xf bank_mask:0xf
	v_mov_b32_dpp v81, v73 quad_perm:[1,0,3,2] row_mask:0xf bank_mask:0xf
	v_mov_b32_dpp v82, v74 quad_perm:[1,0,3,2] row_mask:0xf bank_mask:0xf
	v_mov_b32_dpp v83, v75 quad_perm:[1,0,3,2] row_mask:0xf bank_mask:0xf
	v_mov_b32_dpp v84, v76 quad_perm:[1,0,3,2] row_mask:0xf bank_mask:0xf
	v_mov_b32_dpp v85, v77 quad_perm:[1,0,3,2] row_mask:0xf bank_mask:0xf
	v_mov_b32_dpp v86, v78 quad_perm:[1,0,3,2] row_mask:0xf bank_mask:0xf
	v_mov_b32_dpp v87, v79 quad_perm:[1,0,3,2] row_mask:0xf bank_mask:0xf
	s_nop 0
	v_mul_f32_e32 v80, v80, v117
	v_mul_f32_e32 v81, v81, v119
	v_mul_f32_e32 v82, v82, v121
	v_mul_f32_e32 v83, v83, v123
	v_mul_f32_e32 v84, v84, v125
	v_mul_f32_e32 v85, v85, v127
	v_mul_f32_e32 v86, v86, v129
	v_mul_f32_e32 v87, v87, v131
	v_cndmask_b32_e64 v80, v80, -v80, s[64:65]
	v_cndmask_b32_e64 v81, v81, -v81, s[64:65]
	v_cndmask_b32_e64 v82, v82, -v82, s[64:65]
	v_cndmask_b32_e64 v83, v83, -v83, s[64:65]
	v_cndmask_b32_e64 v84, v84, -v84, s[64:65]
	v_cndmask_b32_e64 v85, v85, -v85, s[64:65]
	v_cndmask_b32_e64 v86, v86, -v86, s[64:65]
	v_cndmask_b32_e64 v87, v87, -v87, s[64:65]
	v_fma_f32 v72, v72, v116, v80
	v_fma_f32 v73, v73, v118, v81
	v_fma_f32 v74, v74, v120, v82
	v_fma_f32 v75, v75, v122, v83
	v_fma_f32 v76, v76, v124, v84
	v_fma_f32 v77, v77, v126, v85
	v_fma_f32 v78, v78, v128, v86
	v_fma_f32 v79, v79, v130, v87
	s_mov_b64 exec, -1
	v_cvt_pk_bf16_f32 v92, v72, v73
	v_cvt_pk_bf16_f32 v93, v74, v75
	v_cvt_pk_bf16_f32 v94, v76, v77
	v_cvt_pk_bf16_f32 v95, v78, v79
	ds_write_b128 v212, v[92:95]
	ds_write_b128 v212, v[20:23] offset:55296
.Lat_skip0_2:
	s_cmp_eq_u32 s53, 0
	s_cbranch_scc1 .Lat_skip1_3
	s_waitcnt vmcnt(24)
	v_lshlrev_b32_e32 v72, 16, v24
	v_and_b32_e32 v73, 0xffff0000, v24
	v_lshlrev_b32_e32 v74, 16, v25
	v_and_b32_e32 v75, 0xffff0000, v25
	v_lshlrev_b32_e32 v76, 16, v26
	v_and_b32_e32 v77, 0xffff0000, v26
	v_lshlrev_b32_e32 v78, 16, v27
	v_and_b32_e32 v79, 0xffff0000, v27
	v_mul_f32_e32 v88, v72, v72
	v_fmac_f32_e32 v88, v73, v73
	v_fmac_f32_e32 v88, v74, v74
	v_fmac_f32_e32 v88, v75, v75
	v_fmac_f32_e32 v88, v76, v76
	v_fmac_f32_e32 v88, v77, v77
	v_fmac_f32_e32 v88, v78, v78
	v_fmac_f32_e32 v88, v79, v79
	s_add_u32 s4, s83, 64
	s_cmpk_ge_u32 s4, 0x180
	s_cselect_b32 s5, 0x180, 0
	s_sub_u32 s4, s4, s5
	s_mul_i32 s4, s4, 0x90
	v_add_f32_dpp v88, v88, v88 quad_perm:[1,0,3,2] row_mask:0xf bank_mask:0xf
	s_nop 1
	v_add_f32_dpp v88, v88, v88 quad_perm:[2,3,0,1] row_mask:0xf bank_mask:0xf
	s_nop 1
	v_add_f32_dpp v88, v88, v88 row_half_mirror row_mask:0xf bank_mask:0xf
	s_nop 1
	v_fmamk_f32 v88, v88, 0x3c800000, v174
	v_rsq_f32_e32 v89, v88
	v_add_u32_e32 v212, s4, v5
	v_mul_f32_e32 v72, v72, v89
	v_mul_f32_e32 v73, v73, v89
	v_mul_f32_e32 v74, v74, v89
	v_mul_f32_e32 v75, v75, v89
	v_mul_f32_e32 v76, v76, v89
	v_mul_f32_e32 v77, v77, v89
	v_mul_f32_e32 v78, v78, v89
	v_mul_f32_e32 v79, v79, v89
	v_mul_f32_e32 v72, v72, v64
	v_mul_f32_e32 v73, v73, v65
	v_mul_f32_e32 v74, v74, v66
	v_mul_f32_e32 v75, v75, v67
	v_mul_f32_e32 v76, v76, v68
	v_mul_f32_e32 v77, v77, v69
	v_mul_f32_e32 v78, v78, v70
	v_mul_f32_e32 v79, v79, v71
	s_mov_b64 exec, s[62:63]
	s_nop 4
	v_mov_b32_dpp v80, v72 quad_perm:[1,0,3,2] row_mask:0xf bank_mask:0xf
	v_mov_b32_dpp v81, v73 quad_perm:[1,0,3,2] row_mask:0xf bank_mask:0xf
	v_mov_b32_dpp v82, v74 quad_perm:[1,0,3,2] row_mask:0xf bank_mask:0xf
	v_mov_b32_dpp v83, v75 quad_perm:[1,0,3,2] row_mask:0xf bank_mask:0xf
	v_mov_b32_dpp v84, v76 quad_perm:[1,0,3,2] row_mask:0xf bank_mask:0xf
	v_mov_b32_dpp v85, v77 quad_perm:[1,0,3,2] row_mask:0xf bank_mask:0xf
	v_mov_b32_dpp v86, v78 quad_perm:[1,0,3,2] row_mask:0xf bank_mask:0xf
	v_mov_b32_dpp v87, v79 quad_perm:[1,0,3,2] row_mask:0xf bank_mask:0xf
	s_nop 0
	v_mul_f32_e32 v80, v80, v133
	v_mul_f32_e32 v81, v81, v135
	v_mul_f32_e32 v82, v82, v137
	v_mul_f32_e32 v83, v83, v139
	v_mul_f32_e32 v84, v84, v141
	v_mul_f32_e32 v85, v85, v143
	v_mul_f32_e32 v86, v86, v145
	v_mul_f32_e32 v87, v87, v147
	v_cndmask_b32_e64 v80, v80, -v80, s[64:65]
	v_cndmask_b32_e64 v81, v81, -v81, s[64:65]
	v_cndmask_b32_e64 v82, v82, -v82, s[64:65]
	v_cndmask_b32_e64 v83, v83, -v83, s[64:65]
	v_cndmask_b32_e64 v84, v84, -v84, s[64:65]
	v_cndmask_b32_e64 v85, v85, -v85, s[64:65]
	v_cndmask_b32_e64 v86, v86, -v86, s[64:65]
	v_cndmask_b32_e64 v87, v87, -v87, s[64:65]
	v_fma_f32 v72, v72, v132, v80
	v_fma_f32 v73, v73, v134, v81
	v_fma_f32 v74, v74, v136, v82
	v_fma_f32 v75, v75, v138, v83
	v_fma_f32 v76, v76, v140, v84
	v_fma_f32 v77, v77, v142, v85
	v_fma_f32 v78, v78, v144, v86
	v_fma_f32 v79, v79, v146, v87
	s_mov_b64 exec, -1
	v_cvt_pk_bf16_f32 v92, v72, v73
	v_cvt_pk_bf16_f32 v93, v74, v75
	v_cvt_pk_bf16_f32 v94, v76, v77
	v_cvt_pk_bf16_f32 v95, v78, v79
	ds_write_b128 v212, v[92:95]
	ds_write_b128 v212, v[28:31] offset:55296
.Lat_skip1_3:
	global_load_dwordx4 v[116:119], v12, s[72:73] offset:0
	global_load_dwordx4 v[120:123], v12, s[72:73] offset:16
	global_load_dwordx4 v[124:127], v12, s[72:73] offset:32
	global_load_dwordx4 v[128:131], v12, s[72:73] offset:48
	global_load_dwordx4 v[132:135], v12, s[72:73] offset:2048
	global_load_dwordx4 v[136:139], v12, s[72:73] offset:2064
	global_load_dwordx4 v[140:143], v12, s[72:73] offset:2080
	global_load_dwordx4 v[144:147], v12, s[72:73] offset:2096
	s_waitcnt vmcnt(26)
	v_lshlrev_b32_e32 v72, 16, v32
	v_and_b32_e32 v73, 0xffff0000, v32
	v_lshlrev_b32_e32 v74, 16, v33
	v_and_b32_e32 v75, 0xffff0000, v33
	v_lshlrev_b32_e32 v76, 16, v34
	v_and_b32_e32 v77, 0xffff0000, v34
	v_lshlrev_b32_e32 v78, 16, v35
	v_and_b32_e32 v79, 0xffff0000, v35
	v_mul_f32_e32 v88, v72, v72
	v_fmac_f32_e32 v88, v73, v73
	v_fmac_f32_e32 v88, v74, v74
	v_fmac_f32_e32 v88, v75, v75
	v_fmac_f32_e32 v88, v76, v76
	v_fmac_f32_e32 v88, v77, v77
	v_fmac_f32_e32 v88, v78, v78
	v_fmac_f32_e32 v88, v79, v79
	s_add_u32 s4, s83, 128
	s_cmpk_ge_u32 s4, 0x180
	s_cselect_b32 s5, 0x180, 0
	s_sub_u32 s4, s4, s5
	s_mul_i32 s4, s4, 0x90
	v_add_f32_dpp v88, v88, v88 quad_perm:[1,0,3,2] row_mask:0xf bank_mask:0xf
	s_nop 1
	v_add_f32_dpp v88, v88, v88 quad_perm:[2,3,0,1] row_mask:0xf bank_mask:0xf
	s_nop 1
	v_add_f32_dpp v88, v88, v88 row_half_mirror row_mask:0xf bank_mask:0xf
	s_nop 1
	v_fmamk_f32 v88, v88, 0x3c800000, v174
	v_rsq_f32_e32 v89, v88
	v_add_u32_e32 v212, s4, v5
	v_mul_f32_e32 v72, v72, v89
	v_mul_f32_e32 v73, v73, v89
	v_mul_f32_e32 v74, v74, v89
	v_mul_f32_e32 v75, v75, v89
	v_mul_f32_e32 v76, v76, v89
	v_mul_f32_e32 v77, v77, v89
	v_mul_f32_e32 v78, v78, v89
	v_mul_f32_e32 v79, v79, v89
	v_mul_f32_e32 v72, v72, v64
	v_mul_f32_e32 v73, v73, v65
	v_mul_f32_e32 v74, v74, v66
	v_mul_f32_e32 v75, v75, v67
	v_mul_f32_e32 v76, v76, v68
	v_mul_f32_e32 v77, v77, v69
	v_mul_f32_e32 v78, v78, v70
	v_mul_f32_e32 v79, v79, v71
	s_mov_b64 exec, s[62:63]
	s_nop 4
	v_mov_b32_dpp v80, v72 quad_perm:[1,0,3,2] row_mask:0xf bank_mask:0xf
	v_mov_b32_dpp v81, v73 quad_perm:[1,0,3,2] row_mask:0xf bank_mask:0xf
	v_mov_b32_dpp v82, v74 quad_perm:[1,0,3,2] row_mask:0xf bank_mask:0xf
	v_mov_b32_dpp v83, v75 quad_perm:[1,0,3,2] row_mask:0xf bank_mask:0xf
	v_mov_b32_dpp v84, v76 quad_perm:[1,0,3,2] row_mask:0xf bank_mask:0xf
	v_mov_b32_dpp v85, v77 quad_perm:[1,0,3,2] row_mask:0xf bank_mask:0xf
	v_mov_b32_dpp v86, v78 quad_perm:[1,0,3,2] row_mask:0xf bank_mask:0xf
	v_mov_b32_dpp v87, v79 quad_perm:[1,0,3,2] row_mask:0xf bank_mask:0xf
	s_nop 0
	v_mul_f32_e32 v80, v80, v149
	v_mul_f32_e32 v81, v81, v151
	v_mul_f32_e32 v82, v82, v153
	v_mul_f32_e32 v83, v83, v155
	v_mul_f32_e32 v84, v84, v157
	v_mul_f32_e32 v85, v85, v159
	v_mul_f32_e32 v86, v86, v161
	v_mul_f32_e32 v87, v87, v163
	v_cndmask_b32_e64 v80, v80, -v80, s[64:65]
	v_cndmask_b32_e64 v81, v81, -v81, s[64:65]
	v_cndmask_b32_e64 v82, v82, -v82, s[64:65]
	v_cndmask_b32_e64 v83, v83, -v83, s[64:65]
	v_cndmask_b32_e64 v84, v84, -v84, s[64:65]
	v_cndmask_b32_e64 v85, v85, -v85, s[64:65]
	v_cndmask_b32_e64 v86, v86, -v86, s[64:65]
	v_cndmask_b32_e64 v87, v87, -v87, s[64:65]
	v_fma_f32 v72, v72, v148, v80
	v_fma_f32 v73, v73, v150, v81
	v_fma_f32 v74, v74, v152, v82
	v_fma_f32 v75, v75, v154, v83
	v_fma_f32 v76, v76, v156, v84
	v_fma_f32 v77, v77, v158, v85
	v_fma_f32 v78, v78, v160, v86
	v_fma_f32 v79, v79, v162, v87
	s_mov_b64 exec, -1
	v_cvt_pk_bf16_f32 v92, v72, v73
	v_cvt_pk_bf16_f32 v93, v74, v75
	v_cvt_pk_bf16_f32 v94, v76, v77
	v_cvt_pk_bf16_f32 v95, v78, v79
	ds_write_b128 v212, v[92:95]
	ds_write_b128 v212, v[36:39] offset:55296
.Lat_skip2_4:
	s_waitcnt vmcnt(20)
	v_lshlrev_b32_e32 v72, 16, v40
	v_and_b32_e32 v73, 0xffff0000, v40
	v_lshlrev_b32_e32 v74, 16, v41
	v_and_b32_e32 v75, 0xffff0000, v41
	v_lshlrev_b32_e32 v76, 16, v42
	v_and_b32_e32 v77, 0xffff0000, v42
	v_lshlrev_b32_e32 v78, 16, v43
	v_and_b32_e32 v79, 0xffff0000, v43
	v_mul_f32_e32 v88, v72, v72
	v_fmac_f32_e32 v88, v73, v73
	v_fmac_f32_e32 v88, v74, v74
	v_fmac_f32_e32 v88, v75, v75
	v_fmac_f32_e32 v88, v76, v76
	v_fmac_f32_e32 v88, v77, v77
	v_fmac_f32_e32 v88, v78, v78
	v_fmac_f32_e32 v88, v79, v79
	s_add_u32 s4, s83, 192
	s_cmpk_ge_u32 s4, 0x180
	s_cselect_b32 s5, 0x180, 0
	s_sub_u32 s4, s4, s5
	s_mul_i32 s4, s4, 0x90
	v_add_f32_dpp v88, v88, v88 quad_perm:[1,0,3,2] row_mask:0xf bank_mask:0xf
	s_nop 1
	v_add_f32_dpp v88, v88, v88 quad_perm:[2,3,0,1] row_mask:0xf bank_mask:0xf
	s_nop 1
	v_add_f32_dpp v88, v88, v88 row_half_mirror row_mask:0xf bank_mask:0xf
	s_nop 1
	v_fmamk_f32 v88, v88, 0x3c800000, v174
	v_rsq_f32_e32 v89, v88
	v_add_u32_e32 v212, s4, v5
	v_mul_f32_e32 v72, v72, v89
	v_mul_f32_e32 v73, v73, v89
	v_mul_f32_e32 v74, v74, v89
	v_mul_f32_e32 v75, v75, v89
	v_mul_f32_e32 v76, v76, v89
	v_mul_f32_e32 v77, v77, v89
	v_mul_f32_e32 v78, v78, v89
	v_mul_f32_e32 v79, v79, v89
	v_mul_f32_e32 v72, v72, v64
	v_mul_f32_e32 v73, v73, v65
	v_mul_f32_e32 v74, v74, v66
	v_mul_f32_e32 v75, v75, v67
	v_mul_f32_e32 v76, v76, v68
	v_mul_f32_e32 v77, v77, v69
	v_mul_f32_e32 v78, v78, v70
	v_mul_f32_e32 v79, v79, v71
	s_mov_b64 exec, s[62:63]
	s_nop 4
	v_mov_b32_dpp v80, v72 quad_perm:[1,0,3,2] row_mask:0xf bank_mask:0xf
	v_mov_b32_dpp v81, v73 quad_perm:[1,0,3,2] row_mask:0xf bank_mask:0xf
	v_mov_b32_dpp v82, v74 quad_perm:[1,0,3,2] row_mask:0xf bank_mask:0xf
	v_mov_b32_dpp v83, v75 quad_perm:[1,0,3,2] row_mask:0xf bank_mask:0xf
	v_mov_b32_dpp v84, v76 quad_perm:[1,0,3,2] row_mask:0xf bank_mask:0xf
	v_mov_b32_dpp v85, v77 quad_perm:[1,0,3,2] row_mask:0xf bank_mask:0xf
	v_mov_b32_dpp v86, v78 quad_perm:[1,0,3,2] row_mask:0xf bank_mask:0xf
	v_mov_b32_dpp v87, v79 quad_perm:[1,0,3,2] row_mask:0xf bank_mask:0xf
	s_nop 0
	v_mul_f32_e32 v80, v80, v165
	v_mul_f32_e32 v81, v81, v167
	v_mul_f32_e32 v82, v82, v169
	v_mul_f32_e32 v83, v83, v171
	v_mul_f32_e32 v84, v84, v177
	v_mul_f32_e32 v85, v85, v179
	v_mul_f32_e32 v86, v86, v181
	v_mul_f32_e32 v87, v87, v183
	v_cndmask_b32_e64 v80, v80, -v80, s[64:65]
	v_cndmask_b32_e64 v81, v81, -v81, s[64:65]
	v_cndmask_b32_e64 v82, v82, -v82, s[64:65]
	v_cndmask_b32_e64 v83, v83, -v83, s[64:65]
	v_cndmask_b32_e64 v84, v84, -v84, s[64:65]
	v_cndmask_b32_e64 v85, v85, -v85, s[64:65]
	v_cndmask_b32_e64 v86, v86, -v86, s[64:65]
	v_cndmask_b32_e64 v87, v87, -v87, s[64:65]
	v_fma_f32 v72, v72, v164, v80
	v_fma_f32 v73, v73, v166, v81
	v_fma_f32 v74, v74, v168, v82
	v_fma_f32 v75, v75, v170, v83
	v_fma_f32 v76, v76, v176, v84
	v_fma_f32 v77, v77, v178, v85
	v_fma_f32 v78, v78, v180, v86
	v_fma_f32 v79, v79, v182, v87
	s_mov_b64 exec, -1
	v_cvt_pk_bf16_f32 v92, v72, v73
	v_cvt_pk_bf16_f32 v93, v74, v75
	v_cvt_pk_bf16_f32 v94, v76, v77
	v_cvt_pk_bf16_f32 v95, v78, v79
	ds_write_b128 v212, v[92:95]
	ds_write_b128 v212, v[44:47] offset:55296
.Lat_skip3_5:
	v_lshlrev_b32_e32 v212, 5, v2
	global_load_dwordx4 v[148:151], v212, s[48:49] offset:0
	global_load_dwordx4 v[152:155], v212, s[48:49] offset:16
	global_load_dwordx4 v[156:159], v212, s[48:49] offset:64
	global_load_dwordx4 v[160:163], v212, s[48:49] offset:80
	global_load_dwordx4 v[164:167], v212, s[48:49] offset:128
	global_load_dwordx4 v[168:171], v212, s[48:49] offset:144
	global_load_dwordx4 v[176:179], v212, s[48:49] offset:192
	global_load_dwordx4 v[180:183], v212, s[48:49] offset:208
	s_cmp_eq_u32 s53, 63
	s_cbranch_scc1 .Lat_skip4_6
	s_waitcnt vmcnt(22)
	v_lshlrev_b32_e32 v72, 16, v48
	v_and_b32_e32 v73, 0xffff0000, v48
	v_lshlrev_b32_e32 v74, 16, v49
	v_and_b32_e32 v75, 0xffff0000, v49
	v_lshlrev_b32_e32 v76, 16, v50
	v_and_b32_e32 v77, 0xffff0000, v50
	v_lshlrev_b32_e32 v78, 16, v51
	v_and_b32_e32 v79, 0xffff0000, v51
	v_mul_f32_e32 v88, v72, v72
	v_fmac_f32_e32 v88, v73, v73
	v_fmac_f32_e32 v88, v74, v74
	v_fmac_f32_e32 v88, v75, v75
	v_fmac_f32_e32 v88, v76, v76
	v_fmac_f32_e32 v88, v77, v77
	v_fmac_f32_e32 v88, v78, v78
	v_fmac_f32_e32 v88, v79, v79
	s_add_u32 s4, s83, 256
	s_cmpk_ge_u32 s4, 0x180
	s_cselect_b32 s5, 0x180, 0
	s_sub_u32 s4, s4, s5
	s_mul_i32 s4, s4, 0x90
	v_add_f32_dpp v88, v88, v88 quad_perm:[1,0,3,2] row_mask:0xf bank_mask:0xf
	s_nop 1
	v_add_f32_dpp v88, v88, v88 quad_perm:[2,3,0,1] row_mask:0xf bank_mask:0xf
	s_nop 1
	v_add_f32_dpp v88, v88, v88 row_half_mirror row_mask:0xf bank_mask:0xf
	s_nop 1
	v_fmamk_f32 v88, v88, 0x3c800000, v174
	v_rsq_f32_e32 v89, v88
	v_add_u32_e32 v212, s4, v5
	v_mul_f32_e32 v72, v72, v89
	v_mul_f32_e32 v73, v73, v89
	v_mul_f32_e32 v74, v74, v89
	v_mul_f32_e32 v75, v75, v89
	v_mul_f32_e32 v76, v76, v89
	v_mul_f32_e32 v77, v77, v89
	v_mul_f32_e32 v78, v78, v89
	v_mul_f32_e32 v79, v79, v89
	v_mul_f32_e32 v72, v72, v64
	v_mul_f32_e32 v73, v73, v65
	v_mul_f32_e32 v74, v74, v66
	v_mul_f32_e32 v75, v75, v67
	v_mul_f32_e32 v76, v76, v68
	v_mul_f32_e32 v77, v77, v69
	v_mul_f32_e32 v78, v78, v70
	v_mul_f32_e32 v79, v79, v71
	s_mov_b64 exec, s[62:63]
	s_nop 4
	v_mov_b32_dpp v80, v72 quad_perm:[1,0,3,2] row_mask:0xf bank_mask:0xf
	v_mov_b32_dpp v81, v73 quad_perm:[1,0,3,2] row_mask:0xf bank_mask:0xf
	v_mov_b32_dpp v82, v74 quad_perm:[1,0,3,2] row_mask:0xf bank_mask:0xf
	v_mov_b32_dpp v83, v75 quad_perm:[1,0,3,2] row_mask:0xf bank_mask:0xf
	v_mov_b32_dpp v84, v76 quad_perm:[1,0,3,2] row_mask:0xf bank_mask:0xf
	v_mov_b32_dpp v85, v77 quad_perm:[1,0,3,2] row_mask:0xf bank_mask:0xf
	v_mov_b32_dpp v86, v78 quad_perm:[1,0,3,2] row_mask:0xf bank_mask:0xf
	v_mov_b32_dpp v87, v79 quad_perm:[1,0,3,2] row_mask:0xf bank_mask:0xf
	s_nop 0
	v_mul_f32_e32 v80, v80, v185
	v_mul_f32_e32 v81, v81, v187
	v_mul_f32_e32 v82, v82, v189
	v_mul_f32_e32 v83, v83, v191
	v_mul_f32_e32 v84, v84, v193
	v_mul_f32_e32 v85, v85, v195
	v_mul_f32_e32 v86, v86, v197
	v_mul_f32_e32 v87, v87, v199
	v_cndmask_b32_e64 v80, v80, -v80, s[64:65]
	v_cndmask_b32_e64 v81, v81, -v81, s[64:65]
	v_cndmask_b32_e64 v82, v82, -v82, s[64:65]
	v_cndmask_b32_e64 v83, v83, -v83, s[64:65]
	v_cndmask_b32_e64 v84, v84, -v84, s[64:65]
	v_cndmask_b32_e64 v85, v85, -v85, s[64:65]
	v_cndmask_b32_e64 v86, v86, -v86, s[64:65]
	v_cndmask_b32_e64 v87, v87, -v87, s[64:65]
	v_fma_f32 v72, v72, v184, v80
	v_fma_f32 v73, v73, v186, v81
	v_fma_f32 v74, v74, v188, v82
	v_fma_f32 v75, v75, v190, v83
	v_fma_f32 v76, v76, v192, v84
	v_fma_f32 v77, v77, v194, v85
	v_fma_f32 v78, v78, v196, v86
	v_fma_f32 v79, v79, v198, v87
	s_mov_b64 exec, -1
	v_cvt_pk_bf16_f32 v92, v72, v73
	v_cvt_pk_bf16_f32 v93, v74, v75
	v_cvt_pk_bf16_f32 v94, v76, v77
	v_cvt_pk_bf16_f32 v95, v78, v79
	ds_write_b128 v212, v[92:95]
	ds_write_b128 v212, v[52:55] offset:55296
.Lat_skip4_6:
	s_cmp_eq_u32 s53, 63
	s_cbranch_scc1 .Lat_skip5_7
	s_waitcnt vmcnt(16)
	v_lshlrev_b32_e32 v72, 16, v56
	v_and_b32_e32 v73, 0xffff0000, v56
	v_lshlrev_b32_e32 v74, 16, v57
	v_and_b32_e32 v75, 0xffff0000, v57
	v_lshlrev_b32_e32 v76, 16, v58
	v_and_b32_e32 v77, 0xffff0000, v58
	v_lshlrev_b32_e32 v78, 16, v59
	v_and_b32_e32 v79, 0xffff0000, v59
	v_mul_f32_e32 v88, v72, v72
	v_fmac_f32_e32 v88, v73, v73
	v_fmac_f32_e32 v88, v74, v74
	v_fmac_f32_e32 v88, v75, v75
	v_fmac_f32_e32 v88, v76, v76
	v_fmac_f32_e32 v88, v77, v77
	v_fmac_f32_e32 v88, v78, v78
	v_fmac_f32_e32 v88, v79, v79
	s_add_u32 s4, s83, 320
	s_cmpk_ge_u32 s4, 0x180
	s_cselect_b32 s5, 0x180, 0
	s_sub_u32 s4, s4, s5
	s_mul_i32 s4, s4, 0x90
	v_add_f32_dpp v88, v88, v88 quad_perm:[1,0,3,2] row_mask:0xf bank_mask:0xf
	s_nop 1
	v_add_f32_dpp v88, v88, v88 quad_perm:[2,3,0,1] row_mask:0xf bank_mask:0xf
	s_nop 1
	v_add_f32_dpp v88, v88, v88 row_half_mirror row_mask:0xf bank_mask:0xf
	s_nop 1
	v_fmamk_f32 v88, v88, 0x3c800000, v174
	v_rsq_f32_e32 v89, v88
	v_add_u32_e32 v212, s4, v5
	v_mul_f32_e32 v72, v72, v89
	v_mul_f32_e32 v73, v73, v89
	v_mul_f32_e32 v74, v74, v89
	v_mul_f32_e32 v75, v75, v89
	v_mul_f32_e32 v76, v76, v89
	v_mul_f32_e32 v77, v77, v89
	v_mul_f32_e32 v78, v78, v89
	v_mul_f32_e32 v79, v79, v89
	v_mul_f32_e32 v72, v72, v64
	v_mul_f32_e32 v73, v73, v65
	v_mul_f32_e32 v74, v74, v66
	v_mul_f32_e32 v75, v75, v67
	v_mul_f32_e32 v76, v76, v68
	v_mul_f32_e32 v77, v77, v69
	v_mul_f32_e32 v78, v78, v70
	v_mul_f32_e32 v79, v79, v71
	s_mov_b64 exec, s[62:63]
	s_nop 4
	v_mov_b32_dpp v80, v72 quad_perm:[1,0,3,2] row_mask:0xf bank_mask:0xf
	v_mov_b32_dpp v81, v73 quad_perm:[1,0,3,2] row_mask:0xf bank_mask:0xf
	v_mov_b32_dpp v82, v74 quad_perm:[1,0,3,2] row_mask:0xf bank_mask:0xf
	v_mov_b32_dpp v83, v75 quad_perm:[1,0,3,2] row_mask:0xf bank_mask:0xf
	v_mov_b32_dpp v84, v76 quad_perm:[1,0,3,2] row_mask:0xf bank_mask:0xf
	v_mov_b32_dpp v85, v77 quad_perm:[1,0,3,2] row_mask:0xf bank_mask:0xf
	v_mov_b32_dpp v86, v78 quad_perm:[1,0,3,2] row_mask:0xf bank_mask:0xf
	v_mov_b32_dpp v87, v79 quad_perm:[1,0,3,2] row_mask:0xf bank_mask:0xf
	s_nop 0
	v_mul_f32_e32 v80, v80, v201
	v_mul_f32_e32 v81, v81, v203
	v_mul_f32_e32 v82, v82, v205
	v_mul_f32_e32 v83, v83, v207
	v_mul_f32_e32 v84, v84, v209
	v_mul_f32_e32 v85, v85, v211
	v_mul_f32_e32 v86, v86, v235
	v_mul_f32_e32 v87, v87, v237
	v_cndmask_b32_e64 v80, v80, -v80, s[64:65]
	v_cndmask_b32_e64 v81, v81, -v81, s[64:65]
	v_cndmask_b32_e64 v82, v82, -v82, s[64:65]
	v_cndmask_b32_e64 v83, v83, -v83, s[64:65]
	v_cndmask_b32_e64 v84, v84, -v84, s[64:65]
	v_cndmask_b32_e64 v85, v85, -v85, s[64:65]
	v_cndmask_b32_e64 v86, v86, -v86, s[64:65]
	v_cndmask_b32_e64 v87, v87, -v87, s[64:65]
	v_fma_f32 v72, v72, v200, v80
	v_fma_f32 v73, v73, v202, v81
	v_fma_f32 v74, v74, v204, v82
	v_fma_f32 v75, v75, v206, v83
	v_fma_f32 v76, v76, v208, v84
	v_fma_f32 v77, v77, v210, v85
	v_fma_f32 v78, v78, v234, v86
	v_fma_f32 v79, v79, v236, v87
	s_mov_b64 exec, -1
	v_cvt_pk_bf16_f32 v92, v72, v73
	v_cvt_pk_bf16_f32 v93, v74, v75
	v_cvt_pk_bf16_f32 v94, v76, v77
	v_cvt_pk_bf16_f32 v95, v78, v79
	ds_write_b128 v212, v[92:95]
	ds_write_b128 v212, v[60:63] offset:55296

.Lat_incr_1:
	global_load_dwordx4 v[96:99], v10, s[40:41] offset:0
	global_load_dwordx4 v[100:103], v10, s[40:41] offset:32
	global_load_dwordx4 v[104:107], v10, s[40:41] offset:64
	global_load_dwordx4 v[108:111], v10, s[40:41] offset:96
	global_load_dwordx4 v[238:241], v11, s[40:41] offset:0
	global_load_dwordx4 v[242:245], v11, s[40:41] offset:32
	global_load_dwordx4 v[246:249], v11, s[40:41] offset:64
	global_load_dwordx4 v[222:225], v11, s[40:41] offset:96
	v_lshlrev_b32_e32 v212, 1, v4
	global_load_dwordx4 v[64:67], v212, s[46:47]
	global_load_dwordx4 v[68:71], v212, s[46:47] offset:16
	v_add_u32_e32 v212, 256, v217
	v_max_i32_e32 v212, 0, v212
	v_min_u32_e32 v212, 0x1fff, v212
	v_mul_lo_u32 v172, v212, s60
	v_add_u32_e32 v172, v172, v4
	v_lshlrev_b32_e32 v216, 6, v212
	global_load_dwordx4 v[48:51], v172, s[38:39] offset:2048
	global_load_dwordx4 v[52:55], v172, s[38:39] offset:2560
	s_mov_b64 exec, s[62:63]
	global_load_dwordx4 v[184:187], v216, s[42:43] offset:0
	global_load_dwordx4 v[188:191], v216, s[42:43] offset:16
	global_load_dwordx4 v[192:195], v216, s[42:43] offset:32
	global_load_dwordx4 v[196:199], v216, s[42:43] offset:48
	s_mov_b64 exec, -1
	v_add_u32_e32 v212, 320, v217
	v_max_i32_e32 v212, 0, v212
	v_min_u32_e32 v212, 0x1fff, v212
	v_mul_lo_u32 v172, v212, s60
	v_add_u32_e32 v172, v172, v4
	v_lshlrev_b32_e32 v216, 6, v212
	global_load_dwordx4 v[56:59], v172, s[38:39] offset:2048
	global_load_dwordx4 v[60:63], v172, s[38:39] offset:2560
	s_mov_b64 exec, s[62:63]
	global_load_dwordx4 v[200:203], v216, s[42:43] offset:0
	global_load_dwordx4 v[204:207], v216, s[42:43] offset:16
	global_load_dwordx4 v[208:211], v216, s[42:43] offset:32
	global_load_dwordx4 v[234:237], v216, s[42:43] offset:48
	s_mov_b64 exec, -1
	global_load_dwordx4 v[116:119], v12, s[72:73] offset:0
	global_load_dwordx4 v[120:123], v12, s[72:73] offset:16
	global_load_dwordx4 v[124:127], v12, s[72:73] offset:32
	global_load_dwordx4 v[128:131], v12, s[72:73] offset:48
	global_load_dwordx4 v[132:135], v12, s[72:73] offset:2048
	global_load_dwordx4 v[136:139], v12, s[72:73] offset:2064
	global_load_dwordx4 v[140:143], v12, s[72:73] offset:2080
	global_load_dwordx4 v[144:147], v12, s[72:73] offset:2096
	v_lshlrev_b32_e32 v212, 5, v2
	global_load_dwordx4 v[148:151], v212, s[48:49] offset:0
	global_load_dwordx4 v[152:155], v212, s[48:49] offset:16
	global_load_dwordx4 v[156:159], v212, s[48:49] offset:64
	global_load_dwordx4 v[160:163], v212, s[48:49] offset:80
	global_load_dwordx4 v[164:167], v212, s[48:49] offset:128
	global_load_dwordx4 v[168:171], v212, s[48:49] offset:144
	global_load_dwordx4 v[176:179], v212, s[48:49] offset:192
	global_load_dwordx4 v[180:183], v212, s[48:49] offset:208
	s_cmp_eq_u32 s53, 63
	s_cbranch_scc1 .Lat_skip4_8
	s_waitcnt vmcnt(22)
	v_lshlrev_b32_e32 v72, 16, v48
	v_and_b32_e32 v73, 0xffff0000, v48
	v_lshlrev_b32_e32 v74, 16, v49
	v_and_b32_e32 v75, 0xffff0000, v49
	v_lshlrev_b32_e32 v76, 16, v50
	v_and_b32_e32 v77, 0xffff0000, v50
	v_lshlrev_b32_e32 v78, 16, v51
	v_and_b32_e32 v79, 0xffff0000, v51
	v_mul_f32_e32 v88, v72, v72
	v_fmac_f32_e32 v88, v73, v73
	v_fmac_f32_e32 v88, v74, v74
	v_fmac_f32_e32 v88, v75, v75
	v_fmac_f32_e32 v88, v76, v76
	v_fmac_f32_e32 v88, v77, v77
	v_fmac_f32_e32 v88, v78, v78
	v_fmac_f32_e32 v88, v79, v79
	s_add_u32 s4, s83, 256
	s_cmpk_ge_u32 s4, 0x180
	s_cselect_b32 s5, 0x180, 0
	s_sub_u32 s4, s4, s5
	s_mul_i32 s4, s4, 0x90
	v_add_f32_dpp v88, v88, v88 quad_perm:[1,0,3,2] row_mask:0xf bank_mask:0xf
	s_nop 1
	v_add_f32_dpp v88, v88, v88 quad_perm:[2,3,0,1] row_mask:0xf bank_mask:0xf
	s_nop 1
	v_add_f32_dpp v88, v88, v88 row_half_mirror row_mask:0xf bank_mask:0xf
	s_nop 1
	v_fmamk_f32 v88, v88, 0x3c800000, v174
	v_rsq_f32_e32 v89, v88
	v_add_u32_e32 v212, s4, v5
	v_mul_f32_e32 v72, v72, v89
	v_mul_f32_e32 v73, v73, v89
	v_mul_f32_e32 v74, v74, v89
	v_mul_f32_e32 v75, v75, v89
	v_mul_f32_e32 v76, v76, v89
	v_mul_f32_e32 v77, v77, v89
	v_mul_f32_e32 v78, v78, v89
	v_mul_f32_e32 v79, v79, v89
	v_mul_f32_e32 v72, v72, v64
	v_mul_f32_e32 v73, v73, v65
	v_mul_f32_e32 v74, v74, v66
	v_mul_f32_e32 v75, v75, v67
	v_mul_f32_e32 v76, v76, v68
	v_mul_f32_e32 v77, v77, v69
	v_mul_f32_e32 v78, v78, v70
	v_mul_f32_e32 v79, v79, v71
	s_mov_b64 exec, s[62:63]
	s_nop 4
	v_mov_b32_dpp v80, v72 quad_perm:[1,0,3,2] row_mask:0xf bank_mask:0xf
	v_mov_b32_dpp v81, v73 quad_perm:[1,0,3,2] row_mask:0xf bank_mask:0xf
	v_mov_b32_dpp v82, v74 quad_perm:[1,0,3,2] row_mask:0xf bank_mask:0xf
	v_mov_b32_dpp v83, v75 quad_perm:[1,0,3,2] row_mask:0xf bank_mask:0xf
	v_mov_b32_dpp v84, v76 quad_perm:[1,0,3,2] row_mask:0xf bank_mask:0xf
	v_mov_b32_dpp v85, v77 quad_perm:[1,0,3,2] row_mask:0xf bank_mask:0xf
	v_mov_b32_dpp v86, v78 quad_perm:[1,0,3,2] row_mask:0xf bank_mask:0xf
	v_mov_b32_dpp v87, v79 quad_perm:[1,0,3,2] row_mask:0xf bank_mask:0xf
	s_nop 0
	v_mul_f32_e32 v80, v80, v185
	v_mul_f32_e32 v81, v81, v187
	v_mul_f32_e32 v82, v82, v189
	v_mul_f32_e32 v83, v83, v191
	v_mul_f32_e32 v84, v84, v193
	v_mul_f32_e32 v85, v85, v195
	v_mul_f32_e32 v86, v86, v197
	v_mul_f32_e32 v87, v87, v199
	v_cndmask_b32_e64 v80, v80, -v80, s[64:65]
	v_cndmask_b32_e64 v81, v81, -v81, s[64:65]
	v_cndmask_b32_e64 v82, v82, -v82, s[64:65]
	v_cndmask_b32_e64 v83, v83, -v83, s[64:65]
	v_cndmask_b32_e64 v84, v84, -v84, s[64:65]
	v_cndmask_b32_e64 v85, v85, -v85, s[64:65]
	v_cndmask_b32_e64 v86, v86, -v86, s[64:65]
	v_cndmask_b32_e64 v87, v87, -v87, s[64:65]
	v_fma_f32 v72, v72, v184, v80
	v_fma_f32 v73, v73, v186, v81
	v_fma_f32 v74, v74, v188, v82
	v_fma_f32 v75, v75, v190, v83
	v_fma_f32 v76, v76, v192, v84
	v_fma_f32 v77, v77, v194, v85
	v_fma_f32 v78, v78, v196, v86
	v_fma_f32 v79, v79, v198, v87
	s_mov_b64 exec, -1
	v_cvt_pk_bf16_f32 v92, v72, v73
	v_cvt_pk_bf16_f32 v93, v74, v75
	v_cvt_pk_bf16_f32 v94, v76, v77
	v_cvt_pk_bf16_f32 v95, v78, v79
	ds_write_b128 v212, v[92:95]
	ds_write_b128 v212, v[52:55] offset:55296

.Lat_bar2:
	s_barrier
	s_lshl_b32 s4, s57, 5
	s_add_u32 s4, s4, s70
	s_add_u32 s4, s4, s83
	s_cmpk_ge_u32 s4, 0x180
	s_cselect_b32 s5, 0x180, 0
	s_sub_u32 s69, s4, s5
	s_mul_i32 s4, s69, 0x90
	v_add_u32_e32 v216, s4, v8
	v_add_u32_e32 v217, s4, v9
	ds_read_b128 v[148:151], v216 offset:0
	ds_read_b128 v[152:155], v216 offset:32
	ds_read_b128 v[156:159], v216 offset:64
	ds_read_b128 v[160:163], v216 offset:96
	ds_read_b64_tr_b16 v[176:177], v217 offset:0
	ds_read_b64_tr_b16 v[178:179], v217 offset:1152
	ds_read_b64_tr_b16 v[180:181], v217 offset:2304
	ds_read_b64_tr_b16 v[182:183], v217 offset:3456
	ds_read_b64_tr_b16 v[184:185], v217 offset:64
	ds_read_b64_tr_b16 v[186:187], v217 offset:1216
	ds_read_b64_tr_b16 v[188:189], v217 offset:2368
	ds_read_b64_tr_b16 v[190:191], v217 offset:3520
.Lat_jloop_10:
	s_add_u32 s4, s69, 32
	s_cmpk_ge_u32 s4, 0x180
	s_cselect_b32 s5, 0x180, 0
	s_sub_u32 s84, s4, s5
	s_mul_i32 s4, s84, 0x90
	v_add_u32_e32 v216, s4, v8
	v_add_u32_e32 v217, s4, v9
	s_cmp_eq_u32 s57, 9
	s_cbranch_scc1 .Lat_t1only_12
	s_cmp_eq_u32 s57, 0
	s_cbranch_scc1 .Lat_t0only_13
	s_waitcnt lgkmcnt(8)
	v_mfma_f32_32x32x16_bf16 v[80:95], v[148:151], v[116:119], v[234:249]
	v_mfma_f32_32x32x16_bf16 v[80:95], v[152:155], v[120:123], v[80:95]
	v_mfma_f32_32x32x16_bf16 v[80:95], v[156:159], v[124:127], v[80:95]
	v_mfma_f32_32x32x16_bf16 v[80:95], v[160:163], v[128:131], v[80:95]
	s_cmp_eq_u32 s57, 0
	s_cbranch_scc0 .Lat_nomask_14
	v_cmp_lt_i32_e64 s[74:75], 0, v15
	v_cmp_lt_i32_e64 s[76:77], 1, v15
	v_cmp_lt_i32_e64 s[78:79], 2, v15
	v_cmp_lt_i32_e64 s[80:81], 3, v15
	v_cndmask_b32_e64 v80, v80, v232, s[74:75]
	v_cndmask_b32_e64 v81, v81, v232, s[76:77]
	v_cndmask_b32_e64 v82, v82, v232, s[78:79]
	v_cndmask_b32_e64 v83, v83, v232, s[80:81]
	v_cmp_lt_i32_e64 s[74:75], 8, v15
	v_cmp_lt_i32_e64 s[76:77], 9, v15
	v_cmp_lt_i32_e64 s[78:79], 10, v15
	v_cmp_lt_i32_e64 s[80:81], 11, v15
	v_cndmask_b32_e64 v84, v84, v232, s[74:75]
	v_cndmask_b32_e64 v85, v85, v232, s[76:77]
	v_cndmask_b32_e64 v86, v86, v232, s[78:79]
	v_cndmask_b32_e64 v87, v87, v232, s[80:81]
	v_cmp_lt_i32_e64 s[74:75], 16, v15
	v_cmp_lt_i32_e64 s[76:77], 17, v15
	v_cmp_lt_i32_e64 s[78:79], 18, v15
	v_cmp_lt_i32_e64 s[80:81], 19, v15
	v_cndmask_b32_e64 v88, v88, v232, s[74:75]
	v_cndmask_b32_e64 v89, v89, v232, s[76:77]
	v_cndmask_b32_e64 v90, v90, v232, s[78:79]
	v_cndmask_b32_e64 v91, v91, v232, s[80:81]
	v_cmp_lt_i32_e64 s[74:75], 24, v15
	v_cmp_lt_i32_e64 s[76:77], 25, v15
	v_cmp_lt_i32_e64 s[78:79], 26, v15
	v_cmp_lt_i32_e64 s[80:81], 27, v15
	v_cndmask_b32_e64 v92, v92, v232, s[74:75]
	v_cndmask_b32_e64 v93, v93, v232, s[76:77]
	v_cndmask_b32_e64 v94, v94, v232, s[78:79]
	v_cndmask_b32_e64 v95, v95, v232, s[80:81]

.Lat_nomask_15:
	v_mfma_f32_32x32x16_bf16 v[96:111], v[148:151], v[132:135], v[192:207]
	v_max3_f32 v212, v80, v81, v82
	v_max3_f32 v250, v83, v84, v85
	v_max3_f32 v212, v212, v86, v87
	v_max3_f32 v250, v250, v88, v89
	v_max3_f32 v212, v212, v90, v91
	v_max3_f32 v250, v250, v92, v93
	v_max3_f32 v212, v212, v94, v95
	v_max_f32_e32 v212, v212, v250
	v_mfma_f32_32x32x16_bf16 v[96:111], v[152:155], v[136:139], v[96:111]
	v_mov_b32_e32 v250, v212
	s_nop 1
	v_permlane32_swap_b32_e32 v212, v250
	v_max_f32_e32 v212, v212, v250
	v_cmp_lt_f32_e32 vcc, 0x41000000, v212
	s_cbranch_vccz .Lat_nors_16
	v_max_f32_e32 v212, 0, v212
	v_exp_f32_e64 v172, -v212
	v_sub_f32_e32 v80, v80, v212
	v_sub_f32_e32 v81, v81, v212
	v_sub_f32_e32 v82, v82, v212
	v_sub_f32_e32 v83, v83, v212
	v_sub_f32_e32 v84, v84, v212
	v_sub_f32_e32 v85, v85, v212
	v_sub_f32_e32 v86, v86, v212
	v_sub_f32_e32 v87, v87, v212
	v_sub_f32_e32 v88, v88, v212
	v_sub_f32_e32 v89, v89, v212
	v_sub_f32_e32 v90, v90, v212
	v_sub_f32_e32 v91, v91, v212
	v_sub_f32_e32 v92, v92, v212
	v_sub_f32_e32 v93, v93, v212
	v_sub_f32_e32 v94, v94, v212
	v_sub_f32_e32 v95, v95, v212
	v_sub_f32_e32 v234, v234, v212
	v_sub_f32_e32 v235, v235, v212
	v_sub_f32_e32 v236, v236, v212
	v_sub_f32_e32 v237, v237, v212
	v_sub_f32_e32 v238, v238, v212
	v_sub_f32_e32 v239, v239, v212
	v_sub_f32_e32 v240, v240, v212
	v_sub_f32_e32 v241, v241, v212
	v_sub_f32_e32 v242, v242, v212
	v_sub_f32_e32 v243, v243, v212
	v_sub_f32_e32 v244, v244, v212
	v_sub_f32_e32 v245, v245, v212
	v_sub_f32_e32 v246, v246, v212
	v_sub_f32_e32 v247, v247, v212
	v_sub_f32_e32 v248, v248, v212
	v_sub_f32_e32 v249, v249, v212
	v_mul_f32_e32 v209, v209, v172
	v_mul_f32_e32 v16, v16, v172
	v_mul_f32_e32 v17, v17, v172
	v_mul_f32_e32 v18, v18, v172
	v_mul_f32_e32 v19, v19, v172
	v_mul_f32_e32 v20, v20, v172
	v_mul_f32_e32 v21, v21, v172
	v_mul_f32_e32 v22, v22, v172
	v_mul_f32_e32 v23, v23, v172
	v_mul_f32_e32 v24, v24, v172
	v_mul_f32_e32 v25, v25, v172
	v_mul_f32_e32 v26, v26, v172
	v_mul_f32_e32 v27, v27, v172
	v_mul_f32_e32 v28, v28, v172
	v_mul_f32_e32 v29, v29, v172
	v_mul_f32_e32 v30, v30, v172
	v_mul_f32_e32 v31, v31, v172
	v_mul_f32_e32 v32, v32, v172
	v_mul_f32_e32 v33, v33, v172
	v_mul_f32_e32 v34, v34, v172
	v_mul_f32_e32 v35, v35, v172
	v_mul_f32_e32 v36, v36, v172
	v_mul_f32_e32 v37, v37, v172
	v_mul_f32_e32 v38, v38, v172
	v_mul_f32_e32 v39, v39, v172
	v_mul_f32_e32 v40, v40, v172
	v_mul_f32_e32 v41, v41, v172
	v_mul_f32_e32 v42, v42, v172
	v_mul_f32_e32 v43, v43, v172
	v_mul_f32_e32 v44, v44, v172
	v_mul_f32_e32 v45, v45, v172
	v_mul_f32_e32 v46, v46, v172
	v_mul_f32_e32 v47, v47, v172
.Lat_nors_16:
	v_exp_f32_e32 v80, v80
	v_exp_f32_e32 v81, v81
	v_mfma_f32_32x32x16_bf16 v[96:111], v[156:159], v[140:143], v[96:111]
	v_exp_f32_e32 v82, v82
	v_exp_f32_e32 v83, v83
	v_exp_f32_e32 v84, v84
	v_exp_f32_e32 v85, v85
	v_mfma_f32_32x32x16_bf16 v[96:111], v[160:163], v[144:147], v[96:111]
	ds_read_b128 v[148:151], v216 offset:0
	ds_read_b128 v[152:155], v216 offset:32
	ds_read_b128 v[156:159], v216 offset:64
	ds_read_b128 v[160:163], v216 offset:96
	v_exp_f32_e32 v86, v86
	v_exp_f32_e32 v87, v87
	v_exp_f32_e32 v88, v88
	v_exp_f32_e32 v89, v89
	v_exp_f32_e32 v90, v90
	v_exp_f32_e32 v91, v91
	v_exp_f32_e32 v92, v92
	v_exp_f32_e32 v93, v93
	v_exp_f32_e32 v94, v94
	v_exp_f32_e32 v95, v95
	v_cvt_pk_bf16_f32 v164, v80, v81
	v_cvt_pk_bf16_f32 v165, v82, v83
	v_cvt_pk_bf16_f32 v166, v84, v85
	v_cvt_pk_bf16_f32 v167, v86, v87
	v_cvt_pk_bf16_f32 v168, v88, v89
	v_cvt_pk_bf16_f32 v169, v90, v91
	v_cvt_pk_bf16_f32 v170, v92, v93
	v_cvt_pk_bf16_f32 v171, v94, v95
	s_cmp_eq_u32 s57, 1
	s_cbranch_scc0 .Lat_nomask_17
	v_cmp_lt_i32_e64 s[74:75], 0, v15
	v_cmp_lt_i32_e64 s[76:77], 1, v15
	v_cmp_lt_i32_e64 s[78:79], 2, v15
	v_cmp_lt_i32_e64 s[80:81], 3, v15
	v_cndmask_b32_e64 v96, v96, v232, s[74:75]
	v_cndmask_b32_e64 v97, v97, v232, s[76:77]
	v_cndmask_b32_e64 v98, v98, v232, s[78:79]
	v_cndmask_b32_e64 v99, v99, v232, s[80:81]
	v_cmp_lt_i32_e64 s[74:75], 8, v15
	v_cmp_lt_i32_e64 s[76:77], 9, v15
	v_cmp_lt_i32_e64 s[78:79], 10, v15
	v_cmp_lt_i32_e64 s[80:81], 11, v15
	v_cndmask_b32_e64 v100, v100, v232, s[74:75]
	v_cndmask_b32_e64 v101, v101, v232, s[76:77]
	v_cndmask_b32_e64 v102, v102, v232, s[78:79]
	v_cndmask_b32_e64 v103, v103, v232, s[80:81]
	v_cmp_lt_i32_e64 s[74:75], 16, v15
	v_cmp_lt_i32_e64 s[76:77], 17, v15
	v_cmp_lt_i32_e64 s[78:79], 18, v15
	v_cmp_lt_i32_e64 s[80:81], 19, v15
	v_cndmask_b32_e64 v104, v104, v232, s[74:75]
	v_cndmask_b32_e64 v105, v105, v232, s[76:77]
	v_cndmask_b32_e64 v106, v106, v232, s[78:79]
	v_cndmask_b32_e64 v107, v107, v232, s[80:81]
	v_cmp_lt_i32_e64 s[74:75], 24, v15
	v_cmp_lt_i32_e64 s[76:77], 25, v15
	v_cmp_lt_i32_e64 s[78:79], 26, v15
	v_cmp_lt_i32_e64 s[80:81], 27, v15
	v_cndmask_b32_e64 v108, v108, v232, s[74:75]
	v_cndmask_b32_e64 v109, v109, v232, s[76:77]
	v_cndmask_b32_e64 v110, v110, v232, s[78:79]
	v_cndmask_b32_e64 v111, v111, v232, s[80:81]

.Lat_nomask_18:
	s_waitcnt lgkmcnt(4)
	v_mfma_f32_32x32x16_bf16 v[16:31], v[176:179], v[164:167], v[16:31]
	v_max3_f32 v212, v96, v97, v98
	v_max3_f32 v250, v99, v100, v101
	v_max3_f32 v212, v212, v102, v103
	v_max3_f32 v250, v250, v104, v105
	v_max3_f32 v212, v212, v106, v107
	v_max3_f32 v250, v250, v108, v109
	v_max3_f32 v212, v212, v110, v111
	v_max_f32_e32 v212, v212, v250
	v_mfma_f32_32x32x16_bf16 v[32:47], v[184:187], v[164:167], v[32:47]
	v_mov_b32_e32 v250, v212
	s_nop 1
	v_permlane32_swap_b32_e32 v212, v250
	v_max_f32_e32 v212, v212, v250
	v_cmp_lt_f32_e32 vcc, 0x41000000, v212
	s_cbranch_vccz .Lat_nors_19
	v_max_f32_e32 v212, 0, v212
	v_exp_f32_e64 v172, -v212
	v_sub_f32_e32 v96, v96, v212
	v_sub_f32_e32 v97, v97, v212
	v_sub_f32_e32 v98, v98, v212
	v_sub_f32_e32 v99, v99, v212
	v_sub_f32_e32 v100, v100, v212
	v_sub_f32_e32 v101, v101, v212
	v_sub_f32_e32 v102, v102, v212
	v_sub_f32_e32 v103, v103, v212
	v_sub_f32_e32 v104, v104, v212
	v_sub_f32_e32 v105, v105, v212
	v_sub_f32_e32 v106, v106, v212
	v_sub_f32_e32 v107, v107, v212
	v_sub_f32_e32 v108, v108, v212
	v_sub_f32_e32 v109, v109, v212
	v_sub_f32_e32 v110, v110, v212
	v_sub_f32_e32 v111, v111, v212
	v_sub_f32_e32 v192, v192, v212
	v_sub_f32_e32 v193, v193, v212
	v_sub_f32_e32 v194, v194, v212
	v_sub_f32_e32 v195, v195, v212
	v_sub_f32_e32 v196, v196, v212
	v_sub_f32_e32 v197, v197, v212
	v_sub_f32_e32 v198, v198, v212
	v_sub_f32_e32 v199, v199, v212
	v_sub_f32_e32 v200, v200, v212
	v_sub_f32_e32 v201, v201, v212
	v_sub_f32_e32 v202, v202, v212
	v_sub_f32_e32 v203, v203, v212
	v_sub_f32_e32 v204, v204, v212
	v_sub_f32_e32 v205, v205, v212
	v_sub_f32_e32 v206, v206, v212
	v_sub_f32_e32 v207, v207, v212
	v_mul_f32_e32 v211, v211, v172
	v_mul_f32_e32 v48, v48, v172
	v_mul_f32_e32 v49, v49, v172
	v_mul_f32_e32 v50, v50, v172
	v_mul_f32_e32 v51, v51, v172
	v_mul_f32_e32 v52, v52, v172
	v_mul_f32_e32 v53, v53, v172
	v_mul_f32_e32 v54, v54, v172
	v_mul_f32_e32 v55, v55, v172
	v_mul_f32_e32 v56, v56, v172
	v_mul_f32_e32 v57, v57, v172
	v_mul_f32_e32 v58, v58, v172
	v_mul_f32_e32 v59, v59, v172
	v_mul_f32_e32 v60, v60, v172
	v_mul_f32_e32 v61, v61, v172
	v_mul_f32_e32 v62, v62, v172
	v_mul_f32_e32 v63, v63, v172
	v_mul_f32_e32 v64, v64, v172
	v_mul_f32_e32 v65, v65, v172
	v_mul_f32_e32 v66, v66, v172
	v_mul_f32_e32 v67, v67, v172
	v_mul_f32_e32 v68, v68, v172
	v_mul_f32_e32 v69, v69, v172
	v_mul_f32_e32 v70, v70, v172
	v_mul_f32_e32 v71, v71, v172
	v_mul_f32_e32 v72, v72, v172
	v_mul_f32_e32 v73, v73, v172
	v_mul_f32_e32 v74, v74, v172
	v_mul_f32_e32 v75, v75, v172
	v_mul_f32_e32 v76, v76, v172
	v_mul_f32_e32 v77, v77, v172
	v_mul_f32_e32 v78, v78, v172
	v_mul_f32_e32 v79, v79, v172
.Lat_nors_19:
	v_exp_f32_e32 v96, v96
	v_exp_f32_e32 v97, v97
	v_mfma_f32_32x32x16_bf16 v[16:31], v[180:183], v[168:171], v[16:31]
	v_exp_f32_e32 v98, v98
	v_exp_f32_e32 v99, v99
	v_exp_f32_e32 v100, v100
	v_exp_f32_e32 v101, v101
	v_mfma_f32_32x32x16_bf16 v[32:47], v[188:191], v[168:171], v[32:47]
	v_exp_f32_e32 v102, v102
	v_exp_f32_e32 v103, v103
	v_exp_f32_e32 v104, v104
	v_exp_f32_e32 v105, v105
	v_exp_f32_e32 v106, v106
	v_exp_f32_e32 v107, v107
	v_exp_f32_e32 v108, v108
	v_exp_f32_e32 v109, v109
	v_exp_f32_e32 v110, v110
	v_exp_f32_e32 v111, v111
	v_cvt_pk_bf16_f32 v164, v96, v97
	v_cvt_pk_bf16_f32 v165, v98, v99
	v_cvt_pk_bf16_f32 v166, v100, v101
	v_cvt_pk_bf16_f32 v167, v102, v103
	v_cvt_pk_bf16_f32 v168, v104, v105
	v_cvt_pk_bf16_f32 v169, v106, v107
	v_cvt_pk_bf16_f32 v170, v108, v109
	v_cvt_pk_bf16_f32 v171, v110, v111
	v_mfma_f32_32x32x16_bf16 v[48:63], v[176:179], v[164:167], v[48:63]
	v_add_f32_e32 v212, v80, v81
	v_add_f32_e32 v250, v82, v83
	v_add_f32_e32 v212, v212, v84
	v_add_f32_e32 v250, v250, v85
	v_add_f32_e32 v212, v212, v86
	v_add_f32_e32 v250, v250, v87
	v_add_f32_e32 v212, v212, v88
	v_add_f32_e32 v250, v250, v89
	v_mfma_f32_32x32x16_bf16 v[64:79], v[184:187], v[164:167], v[64:79]
	v_add_f32_e32 v212, v212, v90
	v_add_f32_e32 v250, v250, v91
	v_add_f32_e32 v212, v212, v92
	v_add_f32_e32 v250, v250, v93
	v_add_f32_e32 v212, v212, v94
	v_add_f32_e32 v250, v250, v95
	v_add_f32_e32 v212, v212, v250
	v_add_f32_e32 v209, v209, v212
	v_mfma_f32_32x32x16_bf16 v[48:63], v[180:183], v[168:171], v[48:63]
	v_add_f32_e32 v212, v96, v97
	v_add_f32_e32 v250, v98, v99
	v_add_f32_e32 v212, v212, v100
	v_add_f32_e32 v250, v250, v101
	v_add_f32_e32 v212, v212, v102
	v_add_f32_e32 v250, v250, v103
	v_add_f32_e32 v212, v212, v104
	v_add_f32_e32 v250, v250, v105
	v_mfma_f32_32x32x16_bf16 v[64:79], v[188:191], v[168:171], v[64:79]
	v_add_f32_e32 v212, v212, v106
	v_add_f32_e32 v250, v250, v107
	v_add_f32_e32 v212, v212, v108
	v_add_f32_e32 v250, v250, v109
	v_add_f32_e32 v212, v212, v110
	v_add_f32_e32 v250, v250, v111
	v_add_f32_e32 v212, v212, v250
	v_add_f32_e32 v211, v211, v212
	ds_read_b64_tr_b16 v[176:177], v217 offset:0
	ds_read_b64_tr_b16 v[178:179], v217 offset:1152
	ds_read_b64_tr_b16 v[180:181], v217 offset:2304
	ds_read_b64_tr_b16 v[182:183], v217 offset:3456
	ds_read_b64_tr_b16 v[184:185], v217 offset:64
	ds_read_b64_tr_b16 v[186:187], v217 offset:1216
	ds_read_b64_tr_b16 v[188:189], v217 offset:2368
	ds_read_b64_tr_b16 v[190:191], v217 offset:3520
	s_branch .Lat_jnext_11
.Lat_t0only_13:
	s_waitcnt lgkmcnt(8)
	v_mfma_f32_32x32x16_bf16 v[80:95], v[148:151], v[116:119], v[234:249]
	v_mfma_f32_32x32x16_bf16 v[80:95], v[152:155], v[120:123], v[80:95]
	v_mfma_f32_32x32x16_bf16 v[80:95], v[156:159], v[124:127], v[80:95]
	v_mfma_f32_32x32x16_bf16 v[80:95], v[160:163], v[128:131], v[80:95]
	ds_read_b128 v[148:151], v216 offset:0
	ds_read_b128 v[152:155], v216 offset:32
	ds_read_b128 v[156:159], v216 offset:64
	ds_read_b128 v[160:163], v216 offset:96
	s_nop 7
	s_nop 7
	s_cmp_eq_u32 s57, 0
	s_cbranch_scc0 .Lat_nomask_20
	v_cmp_lt_i32_e64 s[74:75], 0, v15
	v_cmp_lt_i32_e64 s[76:77], 1, v15
	v_cmp_lt_i32_e64 s[78:79], 2, v15
	v_cmp_lt_i32_e64 s[80:81], 3, v15
	v_cndmask_b32_e64 v80, v80, v232, s[74:75]
	v_cndmask_b32_e64 v81, v81, v232, s[76:77]
	v_cndmask_b32_e64 v82, v82, v232, s[78:79]
	v_cndmask_b32_e64 v83, v83, v232, s[80:81]
	v_cmp_lt_i32_e64 s[74:75], 8, v15
	v_cmp_lt_i32_e64 s[76:77], 9, v15
	v_cmp_lt_i32_e64 s[78:79], 10, v15
	v_cmp_lt_i32_e64 s[80:81], 11, v15
	v_cndmask_b32_e64 v84, v84, v232, s[74:75]
	v_cndmask_b32_e64 v85, v85, v232, s[76:77]
	v_cndmask_b32_e64 v86, v86, v232, s[78:79]
	v_cndmask_b32_e64 v87, v87, v232, s[80:81]
	v_cmp_lt_i32_e64 s[74:75], 16, v15
	v_cmp_lt_i32_e64 s[76:77], 17, v15
	v_cmp_lt_i32_e64 s[78:79], 18, v15
	v_cmp_lt_i32_e64 s[80:81], 19, v15
	v_cndmask_b32_e64 v88, v88, v232, s[74:75]
	v_cndmask_b32_e64 v89, v89, v232, s[76:77]
	v_cndmask_b32_e64 v90, v90, v232, s[78:79]
	v_cndmask_b32_e64 v91, v91, v232, s[80:81]
	v_cmp_lt_i32_e64 s[74:75], 24, v15
	v_cmp_lt_i32_e64 s[76:77], 25, v15
	v_cmp_lt_i32_e64 s[78:79], 26, v15
	v_cmp_lt_i32_e64 s[80:81], 27, v15
	v_cndmask_b32_e64 v92, v92, v232, s[74:75]
	v_cndmask_b32_e64 v93, v93, v232, s[76:77]
	v_cndmask_b32_e64 v94, v94, v232, s[78:79]
	v_cndmask_b32_e64 v95, v95, v232, s[80:81]

.Lat_nors_22:
	v_exp_f32_e32 v80, v80
	v_exp_f32_e32 v81, v81
	v_exp_f32_e32 v82, v82
	v_exp_f32_e32 v83, v83
	v_exp_f32_e32 v84, v84
	v_exp_f32_e32 v85, v85
	v_exp_f32_e32 v86, v86
	v_exp_f32_e32 v87, v87
	v_exp_f32_e32 v88, v88
	v_exp_f32_e32 v89, v89
	v_exp_f32_e32 v90, v90
	v_exp_f32_e32 v91, v91
	v_exp_f32_e32 v92, v92
	v_exp_f32_e32 v93, v93
	v_exp_f32_e32 v94, v94
	v_exp_f32_e32 v95, v95
	v_cvt_pk_bf16_f32 v164, v80, v81
	v_cvt_pk_bf16_f32 v165, v82, v83
	v_cvt_pk_bf16_f32 v166, v84, v85
	v_cvt_pk_bf16_f32 v167, v86, v87
	v_cvt_pk_bf16_f32 v168, v88, v89
	v_cvt_pk_bf16_f32 v169, v90, v91
	v_cvt_pk_bf16_f32 v170, v92, v93
	v_cvt_pk_bf16_f32 v171, v94, v95
	s_waitcnt lgkmcnt(4)
	v_mfma_f32_32x32x16_bf16 v[16:31], v[176:179], v[164:167], v[16:31]
	v_mfma_f32_32x32x16_bf16 v[32:47], v[184:187], v[164:167], v[32:47]
	v_mfma_f32_32x32x16_bf16 v[16:31], v[180:183], v[168:171], v[16:31]
	v_mfma_f32_32x32x16_bf16 v[32:47], v[188:191], v[168:171], v[32:47]
	v_add_f32_e32 v212, v80, v81
	v_add_f32_e32 v250, v82, v83
	v_add_f32_e32 v212, v212, v84
	v_add_f32_e32 v250, v250, v85
	v_add_f32_e32 v212, v212, v86
	v_add_f32_e32 v250, v250, v87
	v_add_f32_e32 v212, v212, v88
	v_add_f32_e32 v250, v250, v89
	v_add_f32_e32 v212, v212, v90
	v_add_f32_e32 v250, v250, v91
	v_add_f32_e32 v212, v212, v92
	v_add_f32_e32 v250, v250, v93
	v_add_f32_e32 v212, v212, v94
	v_add_f32_e32 v250, v250, v95
	v_add_f32_e32 v212, v212, v250
	v_add_f32_e32 v209, v209, v212
	ds_read_b64_tr_b16 v[176:177], v217 offset:0
	ds_read_b64_tr_b16 v[178:179], v217 offset:1152
	ds_read_b64_tr_b16 v[180:181], v217 offset:2304
	ds_read_b64_tr_b16 v[182:183], v217 offset:3456
	ds_read_b64_tr_b16 v[184:185], v217 offset:64
	ds_read_b64_tr_b16 v[186:187], v217 offset:1216
	ds_read_b64_tr_b16 v[188:189], v217 offset:2368
	ds_read_b64_tr_b16 v[190:191], v217 offset:3520
	s_branch .Lat_jnext_11
.Lat_t1only_12:
	s_waitcnt lgkmcnt(8)
	v_mfma_f32_32x32x16_bf16 v[96:111], v[148:151], v[132:135], v[192:207]
	v_mfma_f32_32x32x16_bf16 v[96:111], v[152:155], v[136:139], v[96:111]
	v_mfma_f32_32x32x16_bf16 v[96:111], v[156:159], v[140:143], v[96:111]
	v_mfma_f32_32x32x16_bf16 v[96:111], v[160:163], v[144:147], v[96:111]
	ds_read_b128 v[148:151], v216 offset:0
	ds_read_b128 v[152:155], v216 offset:32
	ds_read_b128 v[156:159], v216 offset:64
	ds_read_b128 v[160:163], v216 offset:96
	s_nop 7
	s_nop 7
	s_cmp_eq_u32 s57, 1
	s_cbranch_scc0 .Lat_nomask_23
	v_cmp_lt_i32_e64 s[74:75], 0, v15
	v_cmp_lt_i32_e64 s[76:77], 1, v15
	v_cmp_lt_i32_e64 s[78:79], 2, v15
	v_cmp_lt_i32_e64 s[80:81], 3, v15
	v_cndmask_b32_e64 v96, v96, v232, s[74:75]
	v_cndmask_b32_e64 v97, v97, v232, s[76:77]
	v_cndmask_b32_e64 v98, v98, v232, s[78:79]
	v_cndmask_b32_e64 v99, v99, v232, s[80:81]
	v_cmp_lt_i32_e64 s[74:75], 8, v15
	v_cmp_lt_i32_e64 s[76:77], 9, v15
	v_cmp_lt_i32_e64 s[78:79], 10, v15
	v_cmp_lt_i32_e64 s[80:81], 11, v15
	v_cndmask_b32_e64 v100, v100, v232, s[74:75]
	v_cndmask_b32_e64 v101, v101, v232, s[76:77]
	v_cndmask_b32_e64 v102, v102, v232, s[78:79]
	v_cndmask_b32_e64 v103, v103, v232, s[80:81]
	v_cmp_lt_i32_e64 s[74:75], 16, v15
	v_cmp_lt_i32_e64 s[76:77], 17, v15
	v_cmp_lt_i32_e64 s[78:79], 18, v15
	v_cmp_lt_i32_e64 s[80:81], 19, v15
	v_cndmask_b32_e64 v104, v104, v232, s[74:75]
	v_cndmask_b32_e64 v105, v105, v232, s[76:77]
	v_cndmask_b32_e64 v106, v106, v232, s[78:79]
	v_cndmask_b32_e64 v107, v107, v232, s[80:81]
	v_cmp_lt_i32_e64 s[74:75], 24, v15
	v_cmp_lt_i32_e64 s[76:77], 25, v15
	v_cmp_lt_i32_e64 s[78:79], 26, v15
	v_cmp_lt_i32_e64 s[80:81], 27, v15
	v_cndmask_b32_e64 v108, v108, v232, s[74:75]
	v_cndmask_b32_e64 v109, v109, v232, s[76:77]
	v_cndmask_b32_e64 v110, v110, v232, s[78:79]
	v_cndmask_b32_e64 v111, v111, v232, s[80:81]

.Lat_nors_25:
	v_exp_f32_e32 v96, v96
	v_exp_f32_e32 v97, v97
	v_exp_f32_e32 v98, v98
	v_exp_f32_e32 v99, v99
	v_exp_f32_e32 v100, v100
	v_exp_f32_e32 v101, v101
	v_exp_f32_e32 v102, v102
	v_exp_f32_e32 v103, v103
	v_exp_f32_e32 v104, v104
	v_exp_f32_e32 v105, v105
	v_exp_f32_e32 v106, v106
	v_exp_f32_e32 v107, v107
	v_exp_f32_e32 v108, v108
	v_exp_f32_e32 v109, v109
	v_exp_f32_e32 v110, v110
	v_exp_f32_e32 v111, v111
	v_cvt_pk_bf16_f32 v164, v96, v97
	v_cvt_pk_bf16_f32 v165, v98, v99
	v_cvt_pk_bf16_f32 v166, v100, v101
	v_cvt_pk_bf16_f32 v167, v102, v103
	v_cvt_pk_bf16_f32 v168, v104, v105
	v_cvt_pk_bf16_f32 v169, v106, v107
	v_cvt_pk_bf16_f32 v170, v108, v109
	v_cvt_pk_bf16_f32 v171, v110, v111
	s_waitcnt lgkmcnt(4)
	v_mfma_f32_32x32x16_bf16 v[48:63], v[176:179], v[164:167], v[48:63]
	v_mfma_f32_32x32x16_bf16 v[64:79], v[184:187], v[164:167], v[64:79]
	v_mfma_f32_32x32x16_bf16 v[48:63], v[180:183], v[168:171], v[48:63]
	v_mfma_f32_32x32x16_bf16 v[64:79], v[188:191], v[168:171], v[64:79]
	v_add_f32_e32 v212, v96, v97
	v_add_f32_e32 v250, v98, v99
	v_add_f32_e32 v212, v212, v100
	v_add_f32_e32 v250, v250, v101
	v_add_f32_e32 v212, v212, v102
	v_add_f32_e32 v250, v250, v103
	v_add_f32_e32 v212, v212, v104
	v_add_f32_e32 v250, v250, v105
	v_add_f32_e32 v212, v212, v106
	v_add_f32_e32 v250, v250, v107
	v_add_f32_e32 v212, v212, v108
	v_add_f32_e32 v250, v250, v109
	v_add_f32_e32 v212, v212, v110
	v_add_f32_e32 v250, v250, v111
	v_add_f32_e32 v212, v212, v250
	v_add_f32_e32 v211, v211, v212
	ds_read_b64_tr_b16 v[176:177], v217 offset:0
	ds_read_b64_tr_b16 v[178:179], v217 offset:1152
	ds_read_b64_tr_b16 v[180:181], v217 offset:2304
	ds_read_b64_tr_b16 v[182:183], v217 offset:3456
	ds_read_b64_tr_b16 v[184:185], v217 offset:64
	ds_read_b64_tr_b16 v[186:187], v217 offset:1216
	ds_read_b64_tr_b16 v[188:189], v217 offset:2368
	ds_read_b64_tr_b16 v[190:191], v217 offset:3520
.Lat_jnext_11:
	s_mov_b32 s69, s84
	s_add_u32 s57, s57, 1
	s_cmp_lt_u32 s57, s68
	s_cbranch_scc1 .Lat_jloop_10
	s_waitcnt lgkmcnt(0)

.Lat_nextunit:
	s_add_u32 s58, s58, 1
	s_add_u32 s53, s53, 1
	s_add_u32 s4, s82, 1
	s_cmp_ge_u32 s4, 3
	s_cselect_b32 s5, 3, 0
	s_sub_u32 s82, s4, s5
	s_cmp_lt_u32 s58, 4
	s_cbranch_scc1 .Lat_unit
	s_add_u32 s52, s52, s59
	s_cmpk_lt_i32 s52, 0x100
	s_cbranch_scc1 .Lat_chunk
